# third redundant workgroup barrier removed (after the full attention unit, adjacent to the one before the quarter unit since the w_out transposes moved)
# baseline (speedup 1.0000x reference)
; #define LAS __attribute__((address_space(3)))
; __global__ void __launch_bounds__(NWAVES * 64, 2) fwd_megakernel(Args a) {
;     ...
;                 {
;                     LAS float* scr = (LAS float*)(lds + wave * 16384);
;                     constexpr int I_OUT = (DMIX / 64) * (DM / 32);
;                     const int it = ((blockIdx.x & 7) * 24 + (l - 8)) * NWAVES + wave;
;                     if (it < I_OUT) p0_transpose_item<false>(a.w_out, DMIX, DM, WOUT, scr, it, lane);
;                     __syncthreads();
;                 }
;             } else group_wait(gca, 256u, (unsigned*)(ws + WS_BAR));
;             attn_unit(lds, gb * 32 + (l >> 2), 3 + (l & 3), QKVG, a.sinks, a.norm_attn, MIX, SSA);
.LBB0_300:
	s_or_b64 exec, exec, s[0:1]
	s_mul_i32 s0, s33, 24
	s_add_i32 s0, s90, s0
	s_lshl_b32 s0, s0, 3
	v_readlane_b32 s1, v253, 29
	s_add_i32 s0, s0, s1
	s_sub_i32 s0, s0, 64
	s_cmpk_gt_i32 s0, 0x3ff
	s_branch .LBB0_302
